# V reads behind the barrier (6|4 waits) + one static s_setprio 1 for MLA wave group B
# baseline (speedup 1.0000x reference)
.Lmy_B_entry:
	s_setprio 1
	s_mov_b32 s30, 0x20000
	s_mov_b32 s31, 0
	s_mov_b32 s12, 0x1000
	s_mov_b32 s13, 0
	s_lshr_b32 s71, s24, 1
	s_lshr_b32 s79, s25, 2
	s_add_i32 s79, s79, -1
	s_mov_b32 s0, 0x80000
	s_mov_b32 s1, 0
	v_lshl_add_u64 v[24:25], v[16:17], 0, s[0:1]
	s_mov_b32 s0, 0x60000
	v_lshl_add_u64 v[28:29], v[224:225], 0, s[0:1]
	s_mov_b32 s0, 0x4000
	v_lshl_add_u64 v[30:31], v[222:223], 0, s[0:1]
	s_waitcnt lgkmcnt(0)
	v_mfma_f32_32x32x16_bf16 v[82:97], v[218:221], v[4:7], v[66:81]
	v_mfma_f32_32x32x16_bf16 v[98:113], v[214:217], v[4:7], v[66:81]
	v_mfma_f32_32x32x16_bf16 v[82:97], v[210:213], v[8:11], v[82:97]
	v_mfma_f32_32x32x16_bf16 v[98:113], v[206:209], v[8:11], v[98:113]
	v_mfma_f32_32x32x16_bf16 v[82:97], v[202:205], v[12:15], v[82:97]
	v_mfma_f32_32x32x16_bf16 v[98:113], v[198:201], v[12:15], v[98:113]
	v_mfma_f32_32x32x16_bf16 v[82:97], v[194:197], v[130:133], v[82:97]
	v_mfma_f32_32x32x16_bf16 v[98:113], v[190:193], v[130:133], v[98:113]
	v_mfma_f32_32x32x16_bf16 v[82:97], v[186:189], v[134:137], v[82:97]
	v_mfma_f32_32x32x16_bf16 v[98:113], v[182:185], v[134:137], v[98:113]
	v_mfma_f32_32x32x16_bf16 v[82:97], v[178:181], v[138:141], v[82:97]
	v_mfma_f32_32x32x16_bf16 v[98:113], v[174:177], v[138:141], v[98:113]
	v_add_u32_e32 v2, 0x3000, v238
	ds_read_b128 v[218:221], v2
	ds_read_b128 v[214:217], v2 offset:512
	ds_read_b128 v[210:213], v2 offset:2048
	ds_read_b128 v[206:209], v2 offset:2560
	ds_read_b128 v[202:205], v2 offset:4096
	ds_read_b128 v[198:201], v2 offset:4608
	ds_read_b128 v[194:197], v2 offset:6144
	ds_read_b128 v[190:193], v2 offset:6656
	ds_read_b128 v[186:189], v2 offset:8192
	ds_read_b128 v[182:185], v2 offset:8704
	ds_read_b128 v[178:181], v2 offset:10240
	ds_read_b128 v[174:177], v2 offset:10752
	s_nop 7
	v_max3_f32 v19, v82, v83, v84
	v_max3_f32 v26, v85, v86, v87
	v_max3_f32 v19, v19, v88, v89
	v_max3_f32 v26, v26, v90, v91
	v_max3_f32 v19, v19, v92, v93
	v_max3_f32 v26, v26, v94, v95
	v_max3_f32 v19, v19, v96, v97
	v_max3_f32 v26, v26, v98, v99
	v_max3_f32 v19, v19, v100, v101
	v_max3_f32 v26, v26, v102, v103
	v_max3_f32 v19, v19, v104, v105
	v_max3_f32 v26, v26, v106, v107
	v_max3_f32 v19, v19, v108, v109
	v_max3_f32 v26, v26, v110, v111
	v_max3_f32 v19, v19, v112, v113
	v_max_f32_e32 v19, v19, v26
	v_mov_b32_e32 v26, v19
	s_nop 1
	v_permlane32_swap_b32_e32 v19, v26
	v_max_f32_e32 v19, v19, v26
	v_max_f32_e32 v19, v19, v19
	v_mov_b32_e32 v239, v19
	v_xor_b32_e32 v66, 0x80000000, v19
	v_mov_b32_e32 v67, v66
	v_mov_b32_e32 v68, v66
	v_mov_b32_e32 v69, v66
	v_mov_b32_e32 v70, v66
	v_mov_b32_e32 v71, v66
	v_mov_b32_e32 v72, v66
	v_mov_b32_e32 v73, v66
	v_mov_b32_e32 v74, v66
	v_mov_b32_e32 v75, v66
	v_mov_b32_e32 v76, v66
	v_mov_b32_e32 v77, v66
	v_mov_b32_e32 v78, v66
	v_mov_b32_e32 v79, v66
	v_mov_b32_e32 v80, v66
	v_mov_b32_e32 v81, v66
	v_sub_f32_e32 v82, v82, v19
	v_sub_f32_e32 v83, v83, v19
	v_sub_f32_e32 v84, v84, v19
	v_sub_f32_e32 v85, v85, v19
	v_sub_f32_e32 v86, v86, v19
	v_sub_f32_e32 v87, v87, v19
	v_sub_f32_e32 v88, v88, v19
	v_sub_f32_e32 v89, v89, v19
	v_sub_f32_e32 v90, v90, v19
	v_sub_f32_e32 v91, v91, v19
	v_sub_f32_e32 v92, v92, v19
	v_sub_f32_e32 v93, v93, v19
	v_sub_f32_e32 v94, v94, v19
	v_sub_f32_e32 v95, v95, v19
	v_sub_f32_e32 v96, v96, v19
	v_sub_f32_e32 v97, v97, v19
	v_sub_f32_e32 v98, v98, v19
	v_sub_f32_e32 v99, v99, v19
	v_sub_f32_e32 v100, v100, v19
	v_sub_f32_e32 v101, v101, v19
	v_sub_f32_e32 v102, v102, v19
	v_sub_f32_e32 v103, v103, v19
	v_sub_f32_e32 v104, v104, v19
	v_sub_f32_e32 v105, v105, v19
	v_sub_f32_e32 v106, v106, v19
	v_sub_f32_e32 v107, v107, v19
	v_sub_f32_e32 v108, v108, v19
	v_sub_f32_e32 v109, v109, v19
	v_sub_f32_e32 v110, v110, v19
	v_sub_f32_e32 v111, v111, v19
	v_sub_f32_e32 v112, v112, v19
	v_sub_f32_e32 v113, v113, v19
	s_cmp_lt_i32 s79, 1
	s_cbranch_scc1 .Lmy_B_tail
	s_waitcnt lgkmcnt(0)
	v_mov_b32_e32 v2, v237
	v_mfma_f32_32x32x16_bf16 v[142:157], v[218:221], v[4:7], v[66:81]
	v_exp_f32_e32 v82, v82
	v_exp_f32_e32 v83, v83
	v_exp_f32_e32 v84, v84
	v_add_f32_e32 v27, v82, v83
	v_exp_f32_e32 v85, v85
	v_mfma_f32_32x32x16_bf16 v[158:173], v[214:217], v[4:7], v[66:81]
	v_exp_f32_e32 v86, v86
	v_add_f32_e32 v27, v27, v84
	v_exp_f32_e32 v87, v87
	v_add_f32_e32 v27, v27, v85
	v_exp_f32_e32 v88, v88
	v_mfma_f32_32x32x16_bf16 v[142:157], v[210:213], v[8:11], v[142:157]
	v_add_f32_e32 v27, v27, v86
	v_exp_f32_e32 v89, v89
	v_add_f32_e32 v27, v27, v87
	v_add_f32_e32 v27, v27, v88
	v_add_f32_e32 v27, v27, v89
	v_mfma_f32_32x32x16_bf16 v[158:173], v[206:209], v[8:11], v[158:173]
	v_cvt_pk_bf16_f32 v82, v82, v83
	v_cvt_pk_bf16_f32 v83, v84, v85
	v_cvt_pk_bf16_f32 v84, v86, v87
	v_cvt_pk_bf16_f32 v85, v88, v89
	v_mfma_f32_32x32x16_bf16 v[142:157], v[202:205], v[12:15], v[142:157]
	v_exp_f32_e32 v90, v90
	v_exp_f32_e32 v91, v91
	v_exp_f32_e32 v92, v92
	v_add_f32_e32 v27, v27, v90
	v_exp_f32_e32 v93, v93
	v_mfma_f32_32x32x16_bf16 v[158:173], v[198:201], v[12:15], v[158:173]
	v_add_f32_e32 v27, v27, v91
	v_exp_f32_e32 v94, v94
	v_add_f32_e32 v27, v27, v92
	v_exp_f32_e32 v95, v95
	v_add_f32_e32 v27, v27, v93
	s_waitcnt vmcnt(2)
	s_barrier
	v_mfma_f32_32x32x16_bf16 v[142:157], v[194:197], v[130:133], v[142:157]
	s_add_u32 m0, s57, 0x6000
	v_exp_f32_e32 v96, v96
	v_add_f32_e32 v27, v27, v94
	global_load_lds_dwordx4 v[28:29], off
	v_lshl_add_u64 v[28:29], v[28:29], 0, s[30:31]
	v_exp_f32_e32 v97, v97
	v_add_f32_e32 v27, v27, v95
	v_add_f32_e32 v27, v27, v96
	ds_read_b64_tr_b16 v[114:115], v2 offset:49152
	ds_read_b64_tr_b16 v[116:117], v2 offset:49664
	ds_read_b64_tr_b16 v[118:119], v2 offset:50176
	ds_read_b64_tr_b16 v[120:121], v2 offset:50688
	v_mfma_f32_32x32x16_bf16 v[158:173], v[190:193], v[130:133], v[158:173]
	s_add_u32 m0, s40, 0x0
	v_add_f32_e32 v27, v27, v97
	v_cvt_pk_bf16_f32 v90, v90, v91
	global_load_lds_dwordx4 v[24:25], off
	v_lshl_add_u64 v[24:25], v[24:25], 0, s[30:31]
	v_cvt_pk_bf16_f32 v91, v92, v93
	v_cvt_pk_bf16_f32 v92, v94, v95
	v_cvt_pk_bf16_f32 v93, v96, v97
	ds_read_b64_tr_b16 v[122:123], v2 offset:51200
	ds_read_b64_tr_b16 v[124:125], v2 offset:51712
	ds_read_b64_tr_b16 v[126:127], v2 offset:52224
	ds_read_b64_tr_b16 v[128:129], v2 offset:52736
	v_mfma_f32_32x32x16_bf16 v[142:157], v[186:189], v[134:137], v[142:157]
	s_add_u32 m0, s40, 0x3000
	v_exp_f32_e32 v98, v98
	v_exp_f32_e32 v99, v99
	global_load_lds_dwordx4 v[24:25], off
	v_lshl_add_u64 v[24:25], v[24:25], 0, s[30:31]
	v_exp_f32_e32 v100, v100
	v_add_f32_e32 v27, v27, v98
	v_exp_f32_e32 v101, v101
	ds_read_b64_tr_b16 v[240:241], v2 offset:53248
	ds_read_b64_tr_b16 v[242:243], v2 offset:53760
	ds_read_b64_tr_b16 v[244:245], v2 offset:54272
	ds_read_b64_tr_b16 v[246:247], v2 offset:54784
	v_mfma_f32_32x32x16_bf16 v[158:173], v[182:185], v[134:137], v[158:173]
	v_add_f32_e32 v27, v27, v99
	v_exp_f32_e32 v102, v102
	v_add_f32_e32 v27, v27, v100
	v_exp_f32_e32 v103, v103
	v_add_f32_e32 v27, v27, v101
	ds_read_b64_tr_b16 v[248:249], v2 offset:55296
	ds_read_b64_tr_b16 v[250:251], v2 offset:55808
	ds_read_b64_tr_b16 v[20:21], v2 offset:56320
	ds_read_b64_tr_b16 v[22:23], v2 offset:56832
	v_mfma_f32_32x32x16_bf16 v[142:157], v[178:181], v[138:141], v[142:157]
	v_exp_f32_e32 v104, v104
	v_add_f32_e32 v27, v27, v102
	v_exp_f32_e32 v105, v105
	v_add_f32_e32 v27, v27, v103
	v_add_f32_e32 v27, v27, v104
	v_mfma_f32_32x32x16_bf16 v[158:173], v[174:177], v[138:141], v[158:173]
	v_add_f32_e32 v27, v27, v105
	v_cvt_pk_bf16_f32 v98, v98, v99
	v_cvt_pk_bf16_f32 v99, v100, v101
	v_cvt_pk_bf16_f32 v100, v102, v103
	v_cvt_pk_bf16_f32 v101, v104, v105
	s_waitcnt lgkmcnt(0)
	v_add_u32_e32 v2, 0x6000, v238
	v_mfma_f32_32x32x16_bf16 v[34:49], v[82:85], v[114:117], v[34:49]
	v_exp_f32_e32 v106, v106
	v_exp_f32_e32 v107, v107
	v_exp_f32_e32 v108, v108
	v_add_f32_e32 v27, v27, v106
	v_exp_f32_e32 v109, v109
	ds_read_b128 v[218:221], v2
	ds_read_b128 v[214:217], v2 offset:512
	ds_read_b128 v[210:213], v2 offset:2048
	v_mfma_f32_32x32x16_bf16 v[50:65], v[82:85], v[240:243], v[50:65]
	v_add_f32_e32 v27, v27, v107
	v_exp_f32_e32 v110, v110
	v_add_f32_e32 v27, v27, v108
	v_exp_f32_e32 v111, v111
	v_add_f32_e32 v27, v27, v109
	ds_read_b128 v[206:209], v2 offset:2560
	ds_read_b128 v[202:205], v2 offset:4096
	ds_read_b128 v[198:201], v2 offset:4608
	v_mfma_f32_32x32x16_bf16 v[34:49], v[90:93], v[118:121], v[34:49]
	v_exp_f32_e32 v112, v112
	v_add_f32_e32 v27, v27, v110
	v_exp_f32_e32 v113, v113
	v_add_f32_e32 v27, v27, v111
	v_add_f32_e32 v27, v27, v112
	ds_read_b128 v[194:197], v2 offset:6144
	ds_read_b128 v[190:193], v2 offset:6656
	ds_read_b128 v[186:189], v2 offset:8192
	v_mfma_f32_32x32x16_bf16 v[50:65], v[90:93], v[244:247], v[50:65]
	v_add_f32_e32 v27, v27, v113
	v_cvt_pk_bf16_f32 v106, v106, v107
	v_cvt_pk_bf16_f32 v107, v108, v109
	v_cvt_pk_bf16_f32 v108, v110, v111
	v_cvt_pk_bf16_f32 v109, v112, v113
	v_add_f32_e32 v236, v236, v27
	ds_read_b128 v[182:185], v2 offset:8704
	ds_read_b128 v[178:181], v2 offset:10240
	ds_read_b128 v[174:177], v2 offset:10752
	v_mfma_f32_32x32x16_bf16 v[34:49], v[98:101], v[122:125], v[34:49]
	v_max3_f32 v19, v142, v143, v144
	v_max3_f32 v26, v145, v146, v147
	v_max3_f32 v19, v19, v148, v149
	v_max3_f32 v26, v26, v150, v151
	v_mfma_f32_32x32x16_bf16 v[50:65], v[98:101], v[248:251], v[50:65]
	v_max3_f32 v19, v19, v152, v153
	v_max3_f32 v26, v26, v154, v155
	v_max3_f32 v19, v19, v156, v157
	v_max3_f32 v26, v26, v158, v159
	v_mfma_f32_32x32x16_bf16 v[34:49], v[106:109], v[126:129], v[34:49]
	v_max3_f32 v19, v19, v160, v161
	v_max3_f32 v26, v26, v162, v163
	v_max3_f32 v19, v19, v164, v165
	v_max3_f32 v26, v26, v166, v167
	v_mfma_f32_32x32x16_bf16 v[50:65], v[106:109], v[20:23], v[50:65]
	v_max3_f32 v19, v19, v168, v169
	v_max3_f32 v26, v26, v170, v171
	v_max3_f32 v19, v19, v172, v173
	v_max_f32_e32 v19, v19, v26
	v_cmp_lt_f32_e32 vcc, s41, v19
	s_cbranch_vccz .Lmy_nors_31
	s_nop 15
	s_nop 15
	v_mov_b32_e32 v26, v19
	s_nop 1
	v_permlane32_swap_b32_e32 v19, v26
	v_max_f32_e32 v19, v19, v26
	v_max_f32_e32 v19, v19, v19
	v_max_f32_e32 v90, 0, v19
	v_exp_f32_e64 v91, -v90
	v_add_f32_e32 v239, v239, v90
	v_xor_b32_e32 v66, 0x80000000, v239
	v_mov_b32_e32 v67, v66
	v_mov_b32_e32 v68, v66
	v_mov_b32_e32 v69, v66
	v_mov_b32_e32 v70, v66
	v_mov_b32_e32 v71, v66
	v_mov_b32_e32 v72, v66
	v_mov_b32_e32 v73, v66
	v_mov_b32_e32 v74, v66
	v_mov_b32_e32 v75, v66
	v_mov_b32_e32 v76, v66
	v_mov_b32_e32 v77, v66
	v_mov_b32_e32 v78, v66
	v_mov_b32_e32 v79, v66
	v_mov_b32_e32 v80, v66
	v_mov_b32_e32 v81, v66
	v_sub_f32_e32 v142, v142, v90
	v_sub_f32_e32 v143, v143, v90
	v_sub_f32_e32 v144, v144, v90
	v_sub_f32_e32 v145, v145, v90
	v_sub_f32_e32 v146, v146, v90
	v_sub_f32_e32 v147, v147, v90
	v_sub_f32_e32 v148, v148, v90
	v_sub_f32_e32 v149, v149, v90
	v_sub_f32_e32 v150, v150, v90
	v_sub_f32_e32 v151, v151, v90
	v_sub_f32_e32 v152, v152, v90
	v_sub_f32_e32 v153, v153, v90
	v_sub_f32_e32 v154, v154, v90
	v_sub_f32_e32 v155, v155, v90
	v_sub_f32_e32 v156, v156, v90
	v_sub_f32_e32 v157, v157, v90
	v_sub_f32_e32 v158, v158, v90
	v_sub_f32_e32 v159, v159, v90
	v_sub_f32_e32 v160, v160, v90
	v_sub_f32_e32 v161, v161, v90
	v_sub_f32_e32 v162, v162, v90
	v_sub_f32_e32 v163, v163, v90
	v_sub_f32_e32 v164, v164, v90
	v_sub_f32_e32 v165, v165, v90
	v_sub_f32_e32 v166, v166, v90
	v_sub_f32_e32 v167, v167, v90
	v_sub_f32_e32 v168, v168, v90
	v_sub_f32_e32 v169, v169, v90
	v_sub_f32_e32 v170, v170, v90
	v_sub_f32_e32 v171, v171, v90
	v_sub_f32_e32 v172, v172, v90
	v_sub_f32_e32 v173, v173, v90
	v_mul_f32_e32 v236, v236, v91
	s_mov_b64 s[96:97], exec
	s_and_b64 exec, exec, s[8:9]
	ds_write_b32 v235, v91
	s_mov_b64 exec, s[96:97]
	v_lshl_add_u32 v2, v228, 4, s47
	ds_read_b128 v[94:97], v2 offset:0
	s_waitcnt lgkmcnt(0)
	v_mul_f32_e32 v34, v34, v94
	v_mul_f32_e32 v50, v50, v94
	v_mul_f32_e32 v35, v35, v95
	v_mul_f32_e32 v51, v51, v95
	v_mul_f32_e32 v36, v36, v96
	v_mul_f32_e32 v52, v52, v96
	v_mul_f32_e32 v37, v37, v97
	v_mul_f32_e32 v53, v53, v97
	ds_read_b128 v[94:97], v2 offset:32
	s_waitcnt lgkmcnt(0)
	v_mul_f32_e32 v38, v38, v94
	v_mul_f32_e32 v54, v54, v94
	v_mul_f32_e32 v39, v39, v95
	v_mul_f32_e32 v55, v55, v95
	v_mul_f32_e32 v40, v40, v96
	v_mul_f32_e32 v56, v56, v96
	v_mul_f32_e32 v41, v41, v97
	v_mul_f32_e32 v57, v57, v97
	ds_read_b128 v[94:97], v2 offset:64
	s_waitcnt lgkmcnt(0)
	v_mul_f32_e32 v42, v42, v94
	v_mul_f32_e32 v58, v58, v94
	v_mul_f32_e32 v43, v43, v95
	v_mul_f32_e32 v59, v59, v95
	v_mul_f32_e32 v44, v44, v96
	v_mul_f32_e32 v60, v60, v96
	v_mul_f32_e32 v45, v45, v97
	v_mul_f32_e32 v61, v61, v97
	ds_read_b128 v[94:97], v2 offset:96
	s_waitcnt lgkmcnt(0)
	v_mul_f32_e32 v46, v46, v94
	v_mul_f32_e32 v62, v62, v94
	v_mul_f32_e32 v47, v47, v95
	v_mul_f32_e32 v63, v63, v95
	v_mul_f32_e32 v48, v48, v96
	v_mul_f32_e32 v64, v64, v96
	v_mul_f32_e32 v49, v49, v97
	v_mul_f32_e32 v65, v65, v97
